# attention tile loop: m0 save/restore around each LDS-DMA removed (12 SALU per iteration)
# speedup vs baseline: 1.0035x; 1.0003x over previous
.LBB0_424:
	v_add_u32_e32 v86, s76, v206
	ds_read_b128 v[82:85], v86
	ds_read_b128 v[86:89], v86 offset:4096
	s_cmp_gt_u32 s4, 33
	s_cselect_b64 s[6:7], -1, 0
	s_cmp_lt_u32 s4, 34
	s_cselect_b32 s20, s75, 0x230000
	s_lshl_b64 s[8:9], s[20:21], 1
	s_add_u32 s8, s36, s8
	s_addc_u32 s9, s37, s9
	s_add_i32 s5, s77, 0
	v_lshl_add_u64 v[80:81], v[180:181], 1, s[8:9]
	s_add_i32 s8, s5, s42
	s_mov_b32 m0, s8
	s_nop 0
	global_load_lds_dwordx4 v[80:81], off
	v_lshl_add_u64 v[80:81], v[176:177], 1, s[38:39]
	s_mov_b32 m0, s67
	s_nop 0
	global_load_lds_dwordx4 v[80:81], off
	v_lshl_add_u64 v[80:81], v[178:179], 1, s[38:39]
	s_mov_b32 m0, s68
	s_nop 0
	global_load_lds_dwordx4 v[80:81], off
	v_add_f32_e32 v81, 0x41000000, v195
	v_cmp_gt_f32_e32 vcc, v197, v81
	s_cbranch_vccz .LBB0_428
	s_waitcnt lgkmcnt(0)
	ds_bpermute_b32 v80, v204, v197
	v_max_f32_e32 v82, v197, v197
	s_waitcnt lgkmcnt(0)
	v_max_f32_e32 v80, v80, v80
	v_max_f32_e32 v80, v82, v80
	v_mov_b64_e32 v[96:97], v[78:79]
	v_cmp_gt_f32_e32 vcc, v80, v81
	v_mov_b64_e32 v[94:95], v[76:77]
	v_mov_b64_e32 v[92:93], v[74:75]
	v_mov_b64_e32 v[90:91], v[72:73]
	v_mov_b64_e32 v[88:89], v[70:71]
	v_mov_b64_e32 v[86:87], v[68:69]
	v_mov_b64_e32 v[84:85], v[66:67]
	v_mov_b64_e32 v[82:83], v[64:65]
	s_and_saveexec_b64 s[8:9], vcc
	s_cbranch_execz .LBB0_427
	v_sub_f32_e32 v65, v80, v195
	v_exp_f32_e64 v64, -v65
	v_xor_b32_e32 v82, 0x80000000, v80
	v_sub_f32_e32 v127, v127, v65
	v_sub_f32_e32 v126, v126, v65
	v_mul_f32_e32 v196, v196, v64
	v_pk_mul_f32 v[62:63], v[62:63], v[64:65] op_sel_hi:[1,0]
	v_pk_mul_f32 v[60:61], v[60:61], v[64:65] op_sel_hi:[1,0]
	v_pk_mul_f32 v[58:59], v[58:59], v[64:65] op_sel_hi:[1,0]
	v_pk_mul_f32 v[56:57], v[56:57], v[64:65] op_sel_hi:[1,0]
	v_pk_mul_f32 v[54:55], v[54:55], v[64:65] op_sel_hi:[1,0]
	v_pk_mul_f32 v[52:53], v[52:53], v[64:65] op_sel_hi:[1,0]
	v_pk_mul_f32 v[50:51], v[50:51], v[64:65] op_sel_hi:[1,0]
	v_pk_mul_f32 v[48:49], v[48:49], v[64:65] op_sel_hi:[1,0]
	v_pk_mul_f32 v[46:47], v[46:47], v[64:65] op_sel_hi:[1,0]
	v_pk_mul_f32 v[44:45], v[44:45], v[64:65] op_sel_hi:[1,0]
	v_pk_mul_f32 v[42:43], v[42:43], v[64:65] op_sel_hi:[1,0]
	v_pk_mul_f32 v[40:41], v[40:41], v[64:65] op_sel_hi:[1,0]
	v_pk_mul_f32 v[38:39], v[38:39], v[64:65] op_sel_hi:[1,0]
	v_pk_mul_f32 v[36:37], v[36:37], v[64:65] op_sel_hi:[1,0]
	v_pk_mul_f32 v[34:35], v[34:35], v[64:65] op_sel_hi:[1,0]
	v_pk_mul_f32 v[32:33], v[32:33], v[64:65] op_sel_hi:[1,0]
	v_pk_mul_f32 v[30:31], v[30:31], v[64:65] op_sel_hi:[1,0]
	v_pk_mul_f32 v[28:29], v[28:29], v[64:65] op_sel_hi:[1,0]
	v_pk_mul_f32 v[26:27], v[26:27], v[64:65] op_sel_hi:[1,0]
	v_pk_mul_f32 v[24:25], v[24:25], v[64:65] op_sel_hi:[1,0]
	v_pk_mul_f32 v[22:23], v[22:23], v[64:65] op_sel_hi:[1,0]
	v_pk_mul_f32 v[20:21], v[20:21], v[64:65] op_sel_hi:[1,0]
	v_pk_mul_f32 v[18:19], v[18:19], v[64:65] op_sel_hi:[1,0]
	v_pk_mul_f32 v[16:17], v[16:17], v[64:65] op_sel_hi:[1,0]
	v_pk_mul_f32 v[14:15], v[14:15], v[64:65] op_sel_hi:[1,0]
	v_pk_mul_f32 v[12:13], v[12:13], v[64:65] op_sel_hi:[1,0]
	v_pk_mul_f32 v[10:11], v[10:11], v[64:65] op_sel_hi:[1,0]
	v_pk_mul_f32 v[8:9], v[8:9], v[64:65] op_sel_hi:[1,0]
	v_pk_mul_f32 v[6:7], v[6:7], v[64:65] op_sel_hi:[1,0]
	v_pk_mul_f32 v[4:5], v[4:5], v[64:65] op_sel_hi:[1,0]
	v_pk_mul_f32 v[2:3], v[2:3], v[64:65] op_sel_hi:[1,0]
	v_pk_mul_f32 v[0:1], v[0:1], v[64:65] op_sel_hi:[1,0]
	v_sub_f32_e32 v125, v125, v65
	v_sub_f32_e32 v124, v124, v65
	v_sub_f32_e32 v123, v123, v65
	v_sub_f32_e32 v122, v122, v65
	v_sub_f32_e32 v121, v121, v65
	v_sub_f32_e32 v120, v120, v65
	v_sub_f32_e32 v119, v119, v65
	v_sub_f32_e32 v118, v118, v65
	v_sub_f32_e32 v117, v117, v65
	v_sub_f32_e32 v116, v116, v65
	v_sub_f32_e32 v115, v115, v65
	v_sub_f32_e32 v114, v114, v65
	v_sub_f32_e32 v113, v113, v65
	v_sub_f32_e32 v112, v112, v65
	v_sub_f32_e32 v159, v159, v65
	v_sub_f32_e32 v158, v158, v65
	v_sub_f32_e32 v157, v157, v65
	v_sub_f32_e32 v156, v156, v65
	v_sub_f32_e32 v155, v155, v65
	v_sub_f32_e32 v154, v154, v65
	v_sub_f32_e32 v153, v153, v65
	v_sub_f32_e32 v152, v152, v65
	v_sub_f32_e32 v151, v151, v65
	v_sub_f32_e32 v150, v150, v65
	v_sub_f32_e32 v149, v149, v65
	v_sub_f32_e32 v148, v148, v65
	v_sub_f32_e32 v147, v147, v65
	v_sub_f32_e32 v146, v146, v65
	v_sub_f32_e32 v145, v145, v65
	v_sub_f32_e32 v144, v144, v65
	v_add_f32_e32 v81, 0x41000000, v80
	v_mov_b32_e32 v83, v82
	v_mov_b32_e32 v84, v82
	v_mov_b32_e32 v85, v82
	v_mov_b32_e32 v86, v82
	v_mov_b32_e32 v87, v82
	v_mov_b32_e32 v88, v82
	v_mov_b32_e32 v89, v82
	v_mov_b32_e32 v90, v82
	v_mov_b32_e32 v91, v82
	v_mov_b32_e32 v92, v82
	v_mov_b32_e32 v93, v82
	v_mov_b32_e32 v94, v82
	v_mov_b32_e32 v95, v82
	v_mov_b32_e32 v96, v82
	v_mov_b32_e32 v97, v82
	v_mov_b32_e32 v79, v82
	v_mov_b32_e32 v78, v82
	v_mov_b32_e32 v77, v82
	v_mov_b32_e32 v76, v82
	v_mov_b32_e32 v75, v82
	v_mov_b32_e32 v74, v82
	v_mov_b32_e32 v73, v82
	v_mov_b32_e32 v72, v82
	v_mov_b32_e32 v71, v82
	v_mov_b32_e32 v70, v82
	v_mov_b32_e32 v69, v82
	v_mov_b32_e32 v68, v82
	v_mov_b32_e32 v67, v82
	v_mov_b32_e32 v66, v82
	v_mov_b32_e32 v65, v82
	v_mov_b32_e32 v64, v82
	v_mov_b32_e32 v195, v80

.LBB0_429:
	s_add_i32 s8, s76, 0
	v_add_u32_e32 v90, s8, v207
	v_add_u32_e32 v94, s8, v208
	v_add_u32_e32 v194, s8, v209
	s_waitcnt lgkmcnt(1)
	v_mfma_f32_32x32x16_bf16 v[128:143], v[82:85], v[160:163], v[64:79]
	ds_read_b128 v[82:85], v90
	ds_read_b128 v[90:93], v90 offset:4096
	v_exp_f32_e32 v95, v112
	v_exp_f32_e32 v245, v113
	v_exp_f32_e32 v145, v145
	v_exp_f32_e32 v244, v115
	v_exp_f32_e32 v115, v149
	v_cvt_pk_bf16_f32 v112, v95, v245
	s_waitcnt lgkmcnt(2)
	v_mfma_f32_32x32x16_bf16 v[96:111], v[86:89], v[160:163], v[64:79]
	ds_read_b128 v[86:89], v94
	ds_read_b128 v[232:235], v94 offset:4096
	ds_read_b128 v[236:239], v194
	ds_read_b128 v[240:243], v194 offset:4096
	v_exp_f32_e32 v94, v114
	v_exp_f32_e32 v114, v117
	v_exp_f32_e32 v156, v156
	s_add_i32 s8, s77, s76
	v_cvt_pk_bf16_f32 v113, v94, v244
	s_cmpk_eq_i32 s8, 0x2000
	s_waitcnt lgkmcnt(5)
	v_mfma_f32_32x32x16_bf16 v[128:143], v[82:85], v[164:167], v[128:143]
	v_exp_f32_e32 v85, v144
	v_exp_f32_e32 v84, v146
	v_exp_f32_e32 v144, v147
	s_cselect_b32 s9, s71, 0x2000
	v_cvt_pk_bf16_f32 v82, v85, v145
	s_cmpk_lg_i32 s8, 0x6000
	s_cselect_b32 s76, s9, 0
	s_waitcnt lgkmcnt(4)
	v_mfma_f32_32x32x16_bf16 v[96:111], v[90:93], v[164:167], v[96:111]
	v_add_f32_e32 v90, v94, v244
	v_add_f32_e32 v91, v95, v245
	v_add_f32_e32 v92, v84, v144
	v_add_f32_e32 v93, v85, v145
	v_exp_f32_e32 v94, v120
	v_add_f32_e32 v90, v90, v92
	v_add_f32_e32 v91, v91, v93
	v_exp_f32_e32 v92, v116
	v_exp_f32_e32 v93, v148
	s_waitcnt lgkmcnt(3)
	v_mfma_f32_32x32x16_bf16 v[128:143], v[86:89], v[168:171], v[128:143]
	v_add_f32_e32 v87, v90, v91
	v_cvt_pk_bf16_f32 v83, v84, v144
	v_add_f32_e32 v84, v92, v114
	v_add_f32_e32 v85, v93, v115
	v_exp_f32_e32 v86, v119
	v_add_f32_e32 v89, v84, v85
	v_exp_f32_e32 v85, v118
	v_exp_f32_e32 v88, v150
	v_exp_f32_e32 v90, v151
	s_waitcnt lgkmcnt(2)
	v_mfma_f32_32x32x16_bf16 v[96:111], v[232:235], v[168:171], v[96:111]
	v_cvt_pk_bf16_f32 v114, v92, v114
	v_cvt_pk_bf16_f32 v84, v93, v115
	v_add_f32_e32 v95, v85, v86
	v_add_f32_e32 v233, v88, v90
	v_cvt_pk_bf16_f32 v115, v85, v86
	v_cvt_pk_bf16_f32 v85, v88, v90
	ds_read_b64_tr_b16 v[90:91], v213 offset:24576
	ds_read_b64_tr_b16 v[92:93], v213 offset:26624
	v_exp_f32_e32 v232, v121
	v_exp_f32_e32 v88, v152
	v_exp_f32_e32 v86, v153
	ds_read_b64_tr_b16 v[116:117], v214 offset:24576
	ds_read_b64_tr_b16 v[118:119], v214 offset:26624
	ds_read_b64_tr_b16 v[144:145], v213 offset:28672
	ds_read_b64_tr_b16 v[146:147], v213 offset:30720
	v_add_f32_e32 v120, v94, v232
	v_add_f32_e32 v121, v95, v233
	s_waitcnt lgkmcnt(4)
	v_mfma_f32_32x32x16_bf16 v[48:63], v[90:93], v[112:115], v[48:63]
	v_add_f32_e32 v90, v88, v86
	v_add_f32_e32 v91, v89, v87
	v_exp_f32_e32 v234, v122
	v_add_f32_e32 v152, v120, v90
	v_add_f32_e32 v153, v121, v91
	ds_read_b64_tr_b16 v[90:91], v215 offset:24576
	ds_read_b64_tr_b16 v[92:93], v215 offset:26624
	ds_read_b64_tr_b16 v[148:149], v214 offset:28672
	ds_read_b64_tr_b16 v[150:151], v214 offset:30720
	v_exp_f32_e32 v235, v154
	v_exp_f32_e32 v87, v124
	v_exp_f32_e32 v89, v125
	v_mfma_f32_32x32x16_bf16 v[128:143], v[236:239], v[172:175], v[128:143]
	v_exp_f32_e32 v236, v123
	v_exp_f32_e32 v237, v155
	v_add_f32_e32 v239, v152, v153
	v_exp_f32_e32 v238, v159
	s_min_u32 s8, s4, 32
	s_min_u32 s10, s4, 33
	s_lshl_b32 s8, s8, 17
	s_waitcnt lgkmcnt(6)
	v_mfma_f32_32x32x16_bf16 v[32:47], v[116:119], v[112:115], v[32:47]
	ds_read_b64_tr_b16 v[116:117], v248 offset:24576
	ds_read_b64_tr_b16 v[118:119], v248 offset:26624
	ds_read_b64_tr_b16 v[120:121], v215 offset:28672
	ds_read_b64_tr_b16 v[122:123], v215 offset:30720
	ds_read_b64_tr_b16 v[152:153], v248 offset:28672
	ds_read_b64_tr_b16 v[154:155], v248 offset:30720
	s_add_u32 s8, s36, s8
	s_addc_u32 s9, s37, 0
	s_waitcnt lgkmcnt(8)
	v_mfma_f32_32x32x16_bf16 v[16:31], v[90:93], v[112:115], v[16:31]
	v_add_f32_e32 v92, v234, v236
	v_add_f32_e32 v93, v235, v237
	v_cvt_pk_bf16_f32 v90, v94, v232
	v_add_f32_e32 v95, v92, v93
	v_cvt_pk_bf16_f32 v91, v234, v236
	v_cvt_pk_bf16_f32 v92, v87, v89
	v_exp_f32_e32 v94, v158
	s_waitcnt lgkmcnt(4)
	v_mfma_f32_32x32x16_bf16 v[0:15], v[116:119], v[112:115], v[0:15]
	v_exp_f32_e32 v112, v126
	v_exp_f32_e32 v114, v127
	v_add_f32_e32 v113, v87, v89
	v_max_f32_e32 v89, v128, v128
	v_cvt_pk_bf16_f32 v93, v112, v114
	s_nop 1
	v_mfma_f32_32x32x16_bf16 v[48:63], v[144:147], v[90:93], v[48:63]
	v_exp_f32_e32 v144, v157
	v_cvt_pk_bf16_f32 v147, v94, v238
	v_cvt_pk_bf16_f32 v145, v235, v237
	v_add_f32_e32 v115, v156, v144
	v_add_f32_e32 v112, v112, v114
	v_add_f32_e32 v113, v113, v115
	v_add_f32_e32 v114, v94, v238
	v_add_f32_e32 v115, v95, v239
	v_mfma_f32_32x32x16_bf16 v[32:47], v[148:151], v[90:93], v[32:47]
	v_add_f32_e32 v112, v112, v114
	v_add_f32_e32 v113, v113, v115
	v_cvt_pk_bf16_f32 v146, v156, v144
	v_add_f32_e32 v87, v112, v113
	ds_read_b64_tr_b16 v[112:113], v213 offset:32768
	ds_read_b64_tr_b16 v[114:115], v213 offset:34816
	v_add_f32_e32 v194, v196, v87
	v_max_f32_e32 v87, v129, v129
	v_max_f32_e32 v87, v89, v87
	s_waitcnt lgkmcnt(4)
	v_mfma_f32_32x32x16_bf16 v[16:31], v[120:123], v[90:93], v[16:31]
	v_max3_f32 v87, v87, v130, v131
	v_max3_f32 v87, v87, v132, v133
	v_max3_f32 v87, v87, v134, v135
	v_max3_f32 v87, v87, v136, v137
	v_max3_f32 v87, v87, v138, v139
	v_max3_f32 v87, v87, v140, v141
	v_max3_f32 v87, v87, v142, v143
	s_waitcnt lgkmcnt(2)
	v_mfma_f32_32x32x16_bf16 v[0:15], v[152:155], v[90:93], v[0:15]
	ds_read_b64_tr_b16 v[90:91], v214 offset:32768
	ds_read_b64_tr_b16 v[92:93], v214 offset:34816
	ds_read_b64_tr_b16 v[116:117], v213 offset:36864
	ds_read_b64_tr_b16 v[118:119], v213 offset:38912
	v_cvt_pk_bf16_f32 v144, v88, v86
	s_waitcnt lgkmcnt(4)
	v_mfma_f32_32x32x16_bf16 v[48:63], v[112:115], v[82:85], v[48:63]
	ds_read_b64_tr_b16 v[112:113], v215 offset:32768
	ds_read_b64_tr_b16 v[114:115], v215 offset:34816
	ds_read_b64_tr_b16 v[120:121], v214 offset:36864
	ds_read_b64_tr_b16 v[122:123], v214 offset:38912
	s_waitcnt lgkmcnt(6)
	v_mfma_f32_32x32x16_bf16 v[32:47], v[90:93], v[82:85], v[32:47]
	ds_read_b64_tr_b16 v[90:91], v248 offset:32768
	ds_read_b64_tr_b16 v[92:93], v248 offset:34816
	ds_read_b64_tr_b16 v[124:125], v215 offset:36864
	ds_read_b64_tr_b16 v[126:127], v215 offset:38912
	v_mfma_f32_32x32x16_bf16 v[96:111], v[240:243], v[172:175], v[96:111]
	s_waitcnt lgkmcnt(6)
	v_mfma_f32_32x32x16_bf16 v[16:31], v[112:115], v[82:85], v[16:31]
	ds_read_b64_tr_b16 v[112:113], v248 offset:36864
	ds_read_b64_tr_b16 v[114:115], v248 offset:38912
	s_nop 7
	v_max3_f32 v87, v87, v96, v97
	v_max3_f32 v87, v87, v98, v99
	s_waitcnt vmcnt(0)
	s_waitcnt lgkmcnt(0)
	s_barrier
	v_mfma_f32_32x32x16_bf16 v[0:15], v[90:93], v[82:85], v[0:15]
	v_lshl_add_u64 v[82:83], v[180:181], 1, s[8:9]
	s_add_i32 s8, s43, s76
	v_lshl_add_u64 v[82:83], v[82:83], 0, s[24:25]
	s_mov_b32 m0, s8
	s_nop 0
	global_load_lds_dwordx4 v[82:83], off
	s_lshl_b32 s8, s10, 17
	v_max3_f32 v87, v87, v100, v101
	s_add_u32 s8, s26, s8
	v_mfma_f32_32x32x16_bf16 v[48:63], v[116:119], v[144:147], v[48:63]
	v_max3_f32 v87, v87, v102, v103
	s_addc_u32 s9, s27, 0
	v_max3_f32 v87, v87, v104, v105
	s_add_u32 s8, s8, 0x40000
	v_max3_f32 v87, v87, v106, v107
	s_addc_u32 s9, s9, 0
	v_max3_f32 v87, v87, v108, v109
	v_mfma_f32_32x32x16_bf16 v[32:47], v[120:123], v[144:147], v[32:47]
	v_lshl_add_u64 v[82:83], v[176:177], 1, s[8:9]
	s_mov_b32 m0, s65
	s_nop 0
	global_load_lds_dwordx4 v[82:83], off
	v_max3_f32 v87, v87, v110, v111
	v_lshl_add_u64 v[82:83], v[178:179], 1, s[8:9]
	s_mov_b32 m0, s66
	s_nop 0
	global_load_lds_dwordx4 v[82:83], off
	v_add_f32_e32 v87, v195, v87
	v_cmp_gt_f32_e32 vcc, v87, v81
	v_mfma_f32_32x32x16_bf16 v[16:31], v[124:127], v[144:147], v[16:31]
	v_mfma_f32_32x32x16_bf16 v[0:15], v[112:115], v[144:147], v[0:15]
	s_cbranch_vccz .LBB0_423
	ds_bpermute_b32 v82, v204, v87
	v_max_f32_e32 v83, v87, v87
	s_waitcnt lgkmcnt(0)
	v_max_f32_e32 v82, v82, v82
	v_max_f32_e32 v112, v83, v82
	v_cmp_gt_f32_e32 vcc, v112, v81
	s_and_saveexec_b64 s[8:9], vcc
	s_cbranch_execz .LBB0_422
	v_sub_f32_e32 v65, v112, v195
	v_exp_f32_e64 v64, -v65
	v_xor_b32_e32 v80, 0x80000000, v112
	v_mov_b32_e32 v81, v80
	v_sub_f32_e32 v128, v128, v65
	v_mul_f32_e32 v194, v194, v64
	v_pk_mul_f32 v[62:63], v[62:63], v[64:65] op_sel_hi:[1,0]
	v_pk_mul_f32 v[60:61], v[60:61], v[64:65] op_sel_hi:[1,0]
	v_pk_mul_f32 v[58:59], v[58:59], v[64:65] op_sel_hi:[1,0]
	v_pk_mul_f32 v[56:57], v[56:57], v[64:65] op_sel_hi:[1,0]
	v_pk_mul_f32 v[54:55], v[54:55], v[64:65] op_sel_hi:[1,0]
	v_pk_mul_f32 v[52:53], v[52:53], v[64:65] op_sel_hi:[1,0]
	v_pk_mul_f32 v[50:51], v[50:51], v[64:65] op_sel_hi:[1,0]
	v_pk_mul_f32 v[48:49], v[48:49], v[64:65] op_sel_hi:[1,0]
	v_pk_mul_f32 v[46:47], v[46:47], v[64:65] op_sel_hi:[1,0]
	v_pk_mul_f32 v[44:45], v[44:45], v[64:65] op_sel_hi:[1,0]
	v_pk_mul_f32 v[42:43], v[42:43], v[64:65] op_sel_hi:[1,0]
	v_pk_mul_f32 v[40:41], v[40:41], v[64:65] op_sel_hi:[1,0]
	v_pk_mul_f32 v[38:39], v[38:39], v[64:65] op_sel_hi:[1,0]
	v_pk_mul_f32 v[36:37], v[36:37], v[64:65] op_sel_hi:[1,0]
	v_pk_mul_f32 v[34:35], v[34:35], v[64:65] op_sel_hi:[1,0]
	v_pk_mul_f32 v[32:33], v[32:33], v[64:65] op_sel_hi:[1,0]
	v_pk_mul_f32 v[30:31], v[30:31], v[64:65] op_sel_hi:[1,0]
	v_pk_mul_f32 v[28:29], v[28:29], v[64:65] op_sel_hi:[1,0]
	v_pk_mul_f32 v[26:27], v[26:27], v[64:65] op_sel_hi:[1,0]
	v_pk_mul_f32 v[24:25], v[24:25], v[64:65] op_sel_hi:[1,0]
	v_pk_mul_f32 v[22:23], v[22:23], v[64:65] op_sel_hi:[1,0]
	v_pk_mul_f32 v[20:21], v[20:21], v[64:65] op_sel_hi:[1,0]
	v_pk_mul_f32 v[18:19], v[18:19], v[64:65] op_sel_hi:[1,0]
	v_pk_mul_f32 v[16:17], v[16:17], v[64:65] op_sel_hi:[1,0]
	v_pk_mul_f32 v[14:15], v[14:15], v[64:65] op_sel_hi:[1,0]
	v_pk_mul_f32 v[12:13], v[12:13], v[64:65] op_sel_hi:[1,0]
	v_pk_mul_f32 v[10:11], v[10:11], v[64:65] op_sel_hi:[1,0]
	v_pk_mul_f32 v[8:9], v[8:9], v[64:65] op_sel_hi:[1,0]
	v_pk_mul_f32 v[6:7], v[6:7], v[64:65] op_sel_hi:[1,0]
	v_pk_mul_f32 v[4:5], v[4:5], v[64:65] op_sel_hi:[1,0]
	v_pk_mul_f32 v[2:3], v[2:3], v[64:65] op_sel_hi:[1,0]
	v_pk_mul_f32 v[0:1], v[0:1], v[64:65] op_sel_hi:[1,0]
	v_sub_f32_e32 v129, v129, v65
	v_sub_f32_e32 v130, v130, v65
	v_sub_f32_e32 v131, v131, v65
	v_sub_f32_e32 v132, v132, v65
	v_sub_f32_e32 v133, v133, v65
	v_sub_f32_e32 v134, v134, v65
	v_sub_f32_e32 v135, v135, v65
	v_sub_f32_e32 v136, v136, v65
	v_sub_f32_e32 v137, v137, v65
	v_sub_f32_e32 v138, v138, v65
	v_sub_f32_e32 v139, v139, v65
	v_sub_f32_e32 v140, v140, v65
	v_sub_f32_e32 v141, v141, v65
	v_sub_f32_e32 v142, v142, v65
	v_sub_f32_e32 v143, v143, v65
	v_sub_f32_e32 v96, v96, v65
	v_sub_f32_e32 v97, v97, v65
	v_sub_f32_e32 v98, v98, v65
	v_sub_f32_e32 v99, v99, v65
	v_sub_f32_e32 v100, v100, v65
	v_sub_f32_e32 v101, v101, v65
	v_sub_f32_e32 v102, v102, v65
	v_sub_f32_e32 v103, v103, v65
	v_sub_f32_e32 v104, v104, v65
	v_sub_f32_e32 v105, v105, v65
	v_sub_f32_e32 v106, v106, v65
	v_sub_f32_e32 v107, v107, v65
	v_sub_f32_e32 v108, v108, v65
	v_sub_f32_e32 v109, v109, v65
	v_sub_f32_e32 v110, v110, v65
	v_sub_f32_e32 v111, v111, v65
	v_mov_b32_e32 v82, v80
	v_mov_b32_e32 v83, v80
	v_mov_b32_e32 v84, v80
	v_mov_b32_e32 v85, v80
	v_mov_b32_e32 v86, v80
	v_mov_b32_e32 v87, v80
	v_mov_b32_e32 v88, v80
	v_mov_b32_e32 v89, v80
	v_mov_b32_e32 v90, v80
	v_mov_b32_e32 v91, v80
	v_mov_b32_e32 v92, v80
	v_mov_b32_e32 v93, v80
	v_mov_b32_e32 v94, v80
	v_mov_b32_e32 v95, v80
	v_mov_b64_e32 v[64:65], v[80:81]
	v_mov_b32_e32 v195, v112
	v_mov_b64_e32 v[66:67], v[82:83]
	v_mov_b64_e32 v[68:69], v[84:85]
	v_mov_b64_e32 v[70:71], v[86:87]
	v_mov_b64_e32 v[72:73], v[88:89]
	v_mov_b64_e32 v[74:75], v[90:91]
	v_mov_b64_e32 v[76:77], v[92:93]
	v_mov_b64_e32 v[78:79], v[94:95]
	s_branch .LBB0_422
